# v15 + attention K/V L2 warm-up loads three tile-pairs ahead of the register prefetch (counted waits adjusted)
# baseline (speedup 1.0000x reference)
; __device__ __forceinline__ void fx_attn_unit(const Args& A, Frame& F, int bh, int qb, float qkmax) {
;     ...
;     const int NP = NT >> 1, jp0 = jstart >> 1, NPB0 = 2 * qb;
;     FX_PREFETCH(jp0); FX_STAGE(jp0 & 1); if (jp0 + 1 < NP) FX_PREFETCH(jp0 + 1);
.LBB0_699:
	s_add_u32 s0, s30, 0x1000
	s_addc_u32 s1, s31, 0
	s_lshl_b32 s34, s21, 6
	v_add_u32_e32 v6, s34, v178
	v_ashrrev_i32_e32 v7, 31, v6
	v_lshlrev_b64 v[8:9], 13, v[6:7]
	v_lshl_add_u64 v[10:11], s[30:31], 0, v[8:9]
	v_lshlrev_b32_e32 v0, 1, v112
	v_lshl_add_u64 v[10:11], v[10:11], 0, v[0:1]
	v_lshl_add_u64 v[8:9], s[0:1], 0, v[8:9]
	v_or_b32_e32 v7, s34, v110
	v_add_u32_e32 v6, 64, v6
	v_lshl_add_u64 v[8:9], v[8:9], 0, v[0:1]
	global_load_dwordx4 v[94:97], v[10:11], off offset:2048
	global_load_dwordx4 v[98:101], v[8:9], off
	s_lshl_b32 s21, s21, 2
	v_lshlrev_b32_e32 v10, 2, v7
	v_ashrrev_i32_e32 v7, 31, v6
	v_mov_b32_e32 v3, s21
	v_lshlrev_b64 v[6:7], 13, v[6:7]
	s_lshl_b32 s21, s20, 2
	v_lshl_add_u64 v[8:9], s[30:31], 0, v[6:7]
	v_lshl_add_u64 v[6:7], s[0:1], 0, v[6:7]
	s_or_b32 s21, s21, 4
	v_lshl_add_u64 v[8:9], v[8:9], 0, v[0:1]
	global_load_dword v122, v3, s[26:27]
	global_load_dword v215, v10, s[28:29]
	global_load_dwordx4 v[102:105], v[8:9], off offset:2048
	v_lshl_add_u64 v[6:7], v[6:7], 0, v[0:1]
	v_mov_b32_e32 v3, s21
	global_load_dwordx4 v[106:109], v[6:7], off
	global_load_dword v216, v10, s[28:29] offset:256
	s_waitcnt vmcnt(7)
	v_add_f32_e32 v117, v2, v4
	global_load_dword v3, v3, s[26:27]
	s_lshr_b32 s34, s20, 1
	s_bfe_u32 s20, s20, 0x10001
	s_lshr_b32 s25, s25, 1
	s_waitcnt lgkmcnt(0)
	v_sub_f32_e32 v4, v5, v117
	s_mul_i32 s21, s20, 0x4800
	v_lshl_add_u32 v6, s20, 12, v211
	s_add_i32 s20, s34, 1
	v_add_u32_e32 v7, s21, v210
	s_cmp_ge_u32 s20, s25
	s_waitcnt vmcnt(7)
	ds_write_b128 v7, v[94:97]
	s_waitcnt vmcnt(6)
	ds_write_b128 v7, v[98:101] offset:36864
	s_waitcnt vmcnt(3)
	ds_write_b128 v7, v[102:105] offset:9216
	s_waitcnt vmcnt(2)
	ds_write_b128 v7, v[106:109] offset:46080
	v_add_f32_e32 v2, v5, v122
	v_sub_f32_e32 v5, v2, v117
	v_add_f32_e32 v4, v4, v215
	s_waitcnt vmcnt(1)
	v_add_f32_e32 v5, v5, v216
	ds_write2st64_b32 v6, v4, v5 offset1:8
	s_waitcnt vmcnt(0)
	v_mov_b32_e32 v35, v3
	s_cbranch_scc1 .LBB0_701
	s_lshl_b32 s21, s20, 7
	v_add_u32_e32 v4, s21, v178
	v_ashrrev_i32_e32 v5, 31, v4
	v_lshlrev_b64 v[6:7], 13, v[4:5]
	v_lshl_add_u64 v[8:9], s[30:31], 0, v[6:7]
	v_lshl_add_u64 v[8:9], v[8:9], 0, v[0:1]
	v_lshl_add_u64 v[6:7], s[0:1], 0, v[6:7]
	v_or_b32_e32 v5, s21, v110
	v_add_u32_e32 v4, 64, v4
	v_lshl_add_u64 v[6:7], v[6:7], 0, v[0:1]
	global_load_dwordx4 v[94:97], v[8:9], off offset:2048
	global_load_dwordx4 v[98:101], v[6:7], off
	v_lshlrev_b32_e32 v9, 2, v5
	v_ashrrev_i32_e32 v5, 31, v4
	v_lshlrev_b64 v[4:5], 13, v[4:5]
	v_lshl_add_u64 v[6:7], s[30:31], 0, v[4:5]
	v_lshl_add_u64 v[4:5], s[0:1], 0, v[4:5]
	s_lshl_b32 s20, s20, 3
	v_lshl_add_u64 v[4:5], v[4:5], 0, v[0:1]
	v_mov_b32_e32 v8, s20
	v_lshl_add_u64 v[6:7], v[6:7], 0, v[0:1]
	global_load_dwordx4 v[106:109], v[4:5], off
	global_load_dwordx2 v[34:35], v8, s[26:27]
	global_load_dword v215, v9, s[28:29]
	global_load_dwordx4 v[102:105], v[6:7], off offset:2048
	global_load_dword v216, v9, s[28:29] offset:256
	s_mov_b64 s[20:21], 0x300000
	v_lshl_add_u64 v[10:11], v[6:7], 0, s[20:21]
	v_lshl_add_u64 v[12:13], v[4:5], 0, s[20:21]
	s_mov_b64 s[20:21], 0x280000
	v_lshl_add_u64 v[14:15], v[6:7], 0, s[20:21]
	v_lshl_add_u64 v[16:17], v[4:5], 0, s[20:21]
	global_load_dword v219, v[14:15], off offset:2048
	global_load_dword v219, v[10:11], off offset:2048
	global_load_dword v219, v[16:17], off
	global_load_dword v219, v[12:13], off
	s_waitcnt vmcnt(7)
	v_mov_b32_e32 v122, v34

; #define LAS __attribute__((address_space(3)))
; __device__ __forceinline__ s16x4 tr16(LAS unsigned char* p) { return __builtin_bit_cast(s16x4, __builtin_amdgcn_ds_read_tr16_b64_v4i16((LAS v4i16_t*)p)); }
; template <bool BAND>
; __device__ __forceinline__ void fx_tile(LAS unsigned char* Kt, LAS unsigned char* Vt, LAS float* Gt, LAS unsigned char* Qw  , f32x16& o0, f32x16& o1, float& l,
;                                         int j, int tq, int hh, int l31, int q, int p, int blk) {
;     f32x16 s0, s1;
; #pragma unroll
;     for (int rg = 0; rg < 4; ++rg) { const f32x4 g0 = *(const LAS f32x4*)(Gt + 8 * rg + 4 * hh), g1 = *(const LAS f32x4*)(Gt + 32 + 8 * rg + 4 * hh);
; #pragma unroll
;         for (int e = 0; e < 4; ++e) { s0[4 * rg + e] = g0[e]; s1[4 * rg + e] = g1[e]; } }
; #pragma unroll
;     for (int ks = 0; ks < 4; ++ks) { const bf16x8 k0 = *(const LAS bf16x8*)(Kt + l31 * KSTR + (16 * ks + 8 * hh) * 2), k1 = *(const LAS bf16x8*)(Kt + (32 + l31) * KSTR + (16 * ks + 8 * hh) * 2);
;         const bf16x8 qk_ = *(const LAS bf16x8*)(Qw + ks * 1024);
;         s0 = MFMA32(k0, qk_, s0); s1 = MFMA32(k1, qk_, s1); }
;     if (BAND) {
; #pragma unroll
;         for (int rg = 0; rg < 4; ++rg)
; #pragma unroll
;             for (int e = 0; e < 4; ++e) { const int kp = 64 * j + 8 * rg + 4 * hh + e; if (kp > tq) s0[4 * rg + e] = -1e30f; if (kp + 32 > tq) s1[4 * rg + e] = -1e30f; }
;     }
; #pragma unroll
;     for (int e = 0; e < 16; ++e) { s0[e] = __builtin_amdgcn_exp2f(s0[e]); s1[e] = __builtin_amdgcn_exp2f(s1[e]); }
;     float r0 = 0.f, r1 = 0.f, r2 = 0.f, r3 = 0.f;
; #pragma unroll
;     for (int e = 0; e < 16; e += 4) { r0 += s0[e] + s1[e]; r1 += s0[e + 1] + s1[e + 1]; r2 += s0[e + 2] + s1[e + 2]; r3 += s0[e + 3] + s1[e + 3]; }
;     l += (r0 + r1) + (r2 + r3);
;     bf16x8 pf[4]; pf[0] = pack8(s0, 0); pf[1] = pack8(s0, 8); pf[2] = pack8(s1, 0); pf[3] = pack8(s1, 8);
; #pragma unroll
;     for (int kk = 0; kk < 4; ++kk) { const int rowv = 16 * kk + 4 * hh + q;
;         const s16x4 lo0 = tr16(Vt + rowv * KSTR + (16 * blk) * 2 + 8 * p), hi0 = tr16(Vt + (rowv + 8) * KSTR + (16 * blk) * 2 + 8 * p);
;         const s16x4 lo1 = tr16(Vt + rowv * KSTR + (32 + 16 * blk) * 2 + 8 * p), hi1 = tr16(Vt + (rowv + 8) * KSTR + (32 + 16 * blk) * 2 + 8 * p);
;         o0 = MFMA32(cat8(lo0, hi0), pf[kk], o0); o1 = MFMA32(cat8(lo1, hi1), pf[kk], o1); }
.LBB0_703:
	s_and_b32 s23, s34, 1
	s_mul_i32 s21, s23, 0x4800
	s_add_i32 s21, s21, 0
	v_add3_u32 v129, s21, v205, v206
	v_lshl_add_u32 v0, s23, 12, v212
	ds_read_b128 v[36:39], v129
	ds_read_b128 v[62:65], v0
	ds_read_b128 v[66:69], v0 offset:32
	ds_read_b128 v[70:73], v0 offset:64
	ds_read_b128 v[74:77], v0 offset:96
	ds_read_b128 v[140:143], v214
	ds_read_b128 v[40:43], v129 offset:4608
	ds_read_b128 v[44:47], v129 offset:32
	ds_read_b128 v[158:161], v214 offset:1024
	s_waitcnt lgkmcnt(3)
	v_mfma_f32_32x32x16_bf16 v[62:77], v[36:39], v[140:143], v[62:77]
	ds_read_b128 v[78:81], v0 offset:128
	ds_read_b128 v[82:85], v0 offset:160
	ds_read_b128 v[86:89], v0 offset:192
	ds_read_b128 v[90:93], v0 offset:224
	ds_read_b128 v[36:39], v129 offset:4640
	v_add_f32_e32 v218, v34, v35
	s_add_i32 s86, s86, 2
	s_addk_i32 s0, 0x80
	s_cmp_ge_u32 s1, s20
	s_mov_b32 s34, s1
	s_waitcnt lgkmcnt(1)
	v_mfma_f32_32x32x16_bf16 v[78:93], v[40:43], v[140:143], v[78:93]
	v_mfma_f32_32x32x16_bf16 v[62:77], v[44:47], v[158:161], v[62:77]
	s_waitcnt lgkmcnt(0)
	v_mfma_f32_32x32x16_bf16 v[78:93], v[36:39], v[158:161], v[78:93]
	ds_read_b128 v[36:39], v129 offset:64
	ds_read_b128 v[220:223], v214 offset:2048
	ds_read_b128 v[40:43], v129 offset:96
	ds_read_b128 v[224:227], v214 offset:3072
	s_waitcnt lgkmcnt(2)
	v_mfma_f32_32x32x16_bf16 v[62:77], v[36:39], v[220:223], v[62:77]
	ds_read_b128 v[36:39], v129 offset:4672
	ds_read_b128 v[44:47], v129 offset:4704
	s_waitcnt lgkmcnt(1)
	v_mfma_f32_32x32x16_bf16 v[78:93], v[36:39], v[220:223], v[78:93]
	v_mfma_f32_32x32x16_bf16 v[62:77], v[40:43], v[224:227], v[62:77]
	s_waitcnt lgkmcnt(0)
	v_mfma_f32_32x32x16_bf16 v[78:93], v[44:47], v[224:227], v[78:93]
	ds_read_b128 v[50:53], v129 offset:9216
	ds_read_b128 v[34:37], v0 offset:2048
	ds_read_b128 v[38:41], v0 offset:2080
	ds_read_b128 v[42:45], v0 offset:2112
	ds_read_b128 v[46:49], v0 offset:2144
	ds_read_b128 v[162:165], v129 offset:13824
	ds_read_b128 v[166:169], v129 offset:9248
	s_nop 2
	v_exp_f32_e32 v130, v62
	v_exp_f32_e32 v132, v63
	v_exp_f32_e32 v134, v64
	v_exp_f32_e32 v156, v65
	v_exp_f32_e32 v170, v66
	s_waitcnt lgkmcnt(2)
	v_mfma_f32_32x32x16_bf16 v[34:49], v[50:53], v[140:143], v[34:49]
	ds_read_b128 v[50:53], v0 offset:2176
	ds_read_b128 v[54:57], v0 offset:2208
	ds_read_b128 v[58:61], v0 offset:2240
	ds_read_b128 v[62:65], v0 offset:2272
	ds_read_b128 v[228:231], v129 offset:13856
	v_exp_f32_e32 v172, v67
	v_exp_f32_e32 v174, v68
	v_exp_f32_e32 v176, v69
	ds_read_b128 v[66:69], v129 offset:9280
	v_add_u32_e32 v0, s21, v209
	s_waitcnt lgkmcnt(6)
	v_mfma_f32_32x32x16_bf16 v[34:49], v[166:169], v[158:161], v[34:49]
	v_add3_u32 v0, v0, v207, v208
	v_exp_f32_e32 v154, v70
	v_exp_f32_e32 v166, v73
	v_exp_f32_e32 v168, v76
	v_exp_f32_e32 v78, v78
	v_exp_f32_e32 v128, v79
	v_exp_f32_e32 v80, v80
	s_waitcnt lgkmcnt(2)
	v_mfma_f32_32x32x16_bf16 v[50:65], v[162:165], v[140:143], v[50:65]
	v_exp_f32_e32 v162, v71
	v_exp_f32_e32 v164, v72
	v_exp_f32_e32 v136, v81
	v_exp_f32_e32 v138, v82
	v_exp_f32_e32 v140, v83
	v_exp_f32_e32 v142, v84
	v_exp_f32_e32 v144, v85
	s_waitcnt lgkmcnt(0)
	v_mfma_f32_32x32x16_bf16 v[34:49], v[66:69], v[220:223], v[34:49]
	v_exp_f32_e32 v70, v86
	v_exp_f32_e32 v82, v87
	v_exp_f32_e32 v72, v88
	v_exp_f32_e32 v84, v89
	v_exp_f32_e32 v86, v91
	v_exp_f32_e32 v76, v92
	v_exp_f32_e32 v88, v93
	v_mfma_f32_32x32x16_bf16 v[50:65], v[228:231], v[158:161], v[50:65]
	ds_read_b128 v[228:231], v129 offset:13888
	ds_read_b128 v[232:235], v129 offset:9312
	ds_read_b128 v[236:239], v129 offset:13920
	v_exp_f32_e32 v158, v74
	v_exp_f32_e32 v74, v90
	v_exp_f32_e32 v160, v75
	v_exp_f32_e32 v90, v77
	s_waitcnt lgkmcnt(1)
	v_mfma_f32_32x32x16_bf16 v[34:49], v[232:235], v[224:227], v[34:49]
	v_mfma_f32_32x32x16_bf16 v[50:65], v[228:231], v[220:223], v[50:65]
	ds_read_b64_tr_b16 v[220:221], v0 offset:36864
	ds_read_b64_tr_b16 v[222:223], v0 offset:38016
	ds_read_b64_tr_b16 v[230:231], v0 offset:38080
	ds_read_b64_tr_b16 v[228:229], v0 offset:36928
	ds_read_b64_tr_b16 v[240:241], v0 offset:39168
	ds_read_b64_tr_b16 v[242:243], v0 offset:40320
	ds_read_b64_tr_b16 v[246:247], v0 offset:40384
	ds_read_b64_tr_b16 v[244:245], v0 offset:39232
	s_nop 2
	v_exp_f32_e32 v131, v34
	v_exp_f32_e32 v133, v35
	v_exp_f32_e32 v135, v36
	v_exp_f32_e32 v157, v37
	v_cvt_pk_bf16_f32 v34, v130, v132
	v_cvt_pk_bf16_f32 v35, v134, v156
	v_cvt_pk_bf16_f32 v36, v170, v172
	v_cvt_pk_bf16_f32 v37, v174, v176
	s_waitcnt lgkmcnt(8)
	v_mfma_f32_32x32x16_bf16 v[50:65], v[236:239], v[224:227], v[50:65]
	ds_read_b64_tr_b16 v[232:233], v0 offset:41472
	ds_read_b64_tr_b16 v[234:235], v0 offset:42624
	ds_read_b64_tr_b16 v[250:251], v0 offset:42688
	ds_read_b64_tr_b16 v[248:249], v0 offset:41536
	ds_read_b64_tr_b16 v[146:147], v0 offset:43776
	ds_read_b64_tr_b16 v[148:149], v0 offset:44928
	ds_read_b64_tr_b16 v[68:69], v0 offset:44992
	ds_read_b64_tr_b16 v[66:67], v0 offset:43840
	v_exp_f32_e32 v171, v38
	v_exp_f32_e32 v173, v39
	v_exp_f32_e32 v175, v40
	v_exp_f32_e32 v177, v41
	v_exp_f32_e32 v155, v42
	v_exp_f32_e32 v169, v48
	s_waitcnt lgkmcnt(14)
	v_mfma_f32_32x32x16_bf16 v[18:33], v[220:223], v[34:37], v[18:33]
	v_exp_f32_e32 v79, v50
	v_exp_f32_e32 v129, v51
	v_exp_f32_e32 v141, v55
	v_exp_f32_e32 v81, v52
	v_exp_f32_e32 v139, v54
	v_exp_f32_e32 v137, v53
	v_exp_f32_e32 v143, v56
	s_waitcnt lgkmcnt(12)
	v_mfma_f32_32x32x16_bf16 v[2:17], v[228:231], v[34:37], v[2:17]
	v_cvt_pk_bf16_f32 v34, v154, v162
	v_cvt_pk_bf16_f32 v35, v164, v166
	v_cvt_pk_bf16_f32 v36, v158, v160
	v_cvt_pk_bf16_f32 v37, v168, v90
	v_add_f32_e64 v40, v132, v128
	v_add_f32_e64 v41, v133, v129
	v_exp_f32_e32 v145, v57
	v_exp_f32_e32 v71, v58
	s_waitcnt lgkmcnt(10)
; __device__ __forceinline__ s16x4 tr16(LAS unsigned char* p) { return __builtin_bit_cast(s16x4, __builtin_amdgcn_ds_read_tr16_b64_v4i16((LAS v4i16_t*)p)); }
; __device__ __forceinline__ bf16x8 cat8(s16x4 lo, s16x4 hi) { return __builtin_shufflevector(lo, hi, 0, 1, 2, 3, 4, 5, 6, 7); }
; #define MFMA32(a, b, c) __builtin_amdgcn_mfma_f32_32x32x16_bf16((a), (b), (c), 0, 0, 0)
; template <bool BAND>
; __device__ __forceinline__ void fx_tile(LAS unsigned char* Kt, LAS unsigned char* Vt, LAS float* Gt, LAS unsigned char* Qw  , f32x16& o0, f32x16& o1, float& l,
;                                         int j, int tq, int hh, int l31, int q, int p, int blk) {
;     ...
;     for (int e = 0; e < 16; ++e) { s0[e] = __builtin_amdgcn_exp2f(s0[e]); s1[e] = __builtin_amdgcn_exp2f(s1[e]); }
;     float r0 = 0.f, r1 = 0.f, r2 = 0.f, r3 = 0.f;
; #pragma unroll
;     for (int e = 0; e < 16; e += 4) { r0 += s0[e] + s1[e]; r1 += s0[e + 1] + s1[e + 1]; r2 += s0[e + 2] + s1[e + 2]; r3 += s0[e + 3] + s1[e + 3]; }
;     l += (r0 + r1) + (r2 + r3);
;     bf16x8 pf[4]; pf[0] = pack8(s0, 0); pf[1] = pack8(s0, 8); pf[2] = pack8(s1, 0); pf[3] = pack8(s1, 8);
; #pragma unroll
;     for (int kk = 0; kk < 4; ++kk) { const int rowv = 16 * kk + 4 * hh + q;
;         const s16x4 lo0 = tr16(Vt + rowv * KSTR + (16 * blk) * 2 + 8 * p), hi0 = tr16(Vt + (rowv + 8) * KSTR + (16 * blk) * 2 + 8 * p);
;         const s16x4 lo1 = tr16(Vt + rowv * KSTR + (32 + 16 * blk) * 2 + 8 * p), hi1 = tr16(Vt + (rowv + 8) * KSTR + (32 + 16 * blk) * 2 + 8 * p);
;         o0 = MFMA32(cat8(lo0, hi0), pf[kk], o0); o1 = MFMA32(cat8(lo1, hi1), pf[kk], o1); }
; }
; __device__ __forceinline__ void fx_attn_unit(const Args& A, Frame& F, int bh, int qb, float qkmax) {
;     ...
;     const int NP = NT >> 1, jp0 = jstart >> 1, NPB0 = 2 * qb;
;     FX_PREFETCH(jp0); FX_STAGE(jp0 & 1); if (jp0 + 1 < NP) FX_PREFETCH(jp0 + 1);
;     __syncthreads();
;     const int wl = q0 + 32 * wave + 31;
;     int jp = jp0;
;     for (; jp < NPB0; ++jp) {
;         FX_STAGE((jp + 1) & 1); if (jp + 2 < NP) FX_PREFETCH(jp + 2);
	v_mfma_f32_32x32x16_bf16 v[18:33], v[240:243], v[34:37], v[18:33]
	v_add_f32_e64 v40, v40, 0
	v_add_f32_e64 v41, v41, 0
	v_exp_f32_e32 v91, v49
	v_exp_f32_e32 v163, v43
	v_exp_f32_e32 v159, v46
	v_exp_f32_e32 v161, v47
	v_pk_add_f32 v[42:43], v[134:135], v[80:81]
	v_pk_add_f32 v[46:47], v[170:171], v[138:139]
	s_waitcnt lgkmcnt(8)
	v_mfma_f32_32x32x16_bf16 v[2:17], v[244:247], v[34:37], v[2:17]
	v_add_f32_e64 v34, v130, v78
	v_add_f32_e64 v35, v131, v79
	v_cvt_pk_bf16_f32 v36, v138, v140
	v_add_f32_e64 v38, v34, 0
	v_add_f32_e64 v39, v35, 0
	v_cvt_pk_bf16_f32 v34, v78, v128
	v_cvt_pk_bf16_f32 v35, v80, v136
	v_cvt_pk_bf16_f32 v37, v142, v144
	v_exp_f32_e32 v165, v44
	v_exp_f32_e32 v167, v45
	s_waitcnt lgkmcnt(6)
	v_mfma_f32_32x32x16_bf16 v[18:33], v[232:235], v[34:37], v[18:33]
	v_add_f32_e64 v42, v42, 0
	v_add_f32_e64 v43, v43, 0
	v_add_f32_e64 v44, v156, v136
	v_add_f32_e64 v45, v157, v137
	v_add_f32_e64 v46, v46, v38
	v_add_f32_e64 v47, v47, v39
	v_pk_add_f32 v[38:39], v[174:175], v[142:143]
	v_pk_add_f32 v[44:45], v[44:45], 0 op_sel_hi:[1,0]
	v_pk_add_f32 v[50:51], v[38:39], v[42:43]
	v_pk_add_f32 v[38:39], v[176:177], v[144:145]
	s_waitcnt lgkmcnt(4)
	v_mfma_f32_32x32x16_bf16 v[2:17], v[248:251], v[34:37], v[2:17]
	v_add_f32_e64 v34, v172, v140
	v_add_f32_e64 v35, v173, v141
	v_cvt_pk_bf16_f32 v36, v74, v86
	v_add_f32_e64 v48, v34, v40
	v_add_f32_e64 v49, v35, v41
	v_cvt_pk_bf16_f32 v34, v70, v82
	v_cvt_pk_bf16_f32 v35, v72, v84
	v_cvt_pk_bf16_f32 v37, v76, v88
	v_pk_add_f32 v[42:43], v[154:155], v[70:71]
	v_pk_add_f32 v[52:53], v[38:39], v[44:45]
	s_waitcnt lgkmcnt(2)
	v_mfma_f32_32x32x16_bf16 v[18:33], v[146:149], v[34:37], v[18:33]
	ds_read_b64_tr_b16 v[38:39], v0 offset:46080
	ds_read_b64_tr_b16 v[40:41], v0 offset:47232
	v_add_f32_e64 v46, v42, v46
	v_add_f32_e64 v47, v43, v47
	ds_read_b64_tr_b16 v[44:45], v0 offset:47296
	ds_read_b64_tr_b16 v[42:43], v0 offset:46144
	v_exp_f32_e32 v83, v59
	v_exp_f32_e32 v73, v60
	v_exp_f32_e32 v75, v62
	v_exp_f32_e32 v87, v63
	s_waitcnt lgkmcnt(4)
	v_mfma_f32_32x32x16_bf16 v[2:17], v[66:69], v[34:37], v[2:17]
	v_cvt_pk_bf16_f32 v34, v131, v133
	v_cvt_pk_bf16_f32 v35, v135, v157
	v_cvt_pk_bf16_f32 v36, v171, v173
	v_cvt_pk_bf16_f32 v37, v175, v177
	v_exp_f32_e32 v85, v61
	v_exp_f32_e32 v77, v64
	v_exp_f32_e32 v89, v65
	s_waitcnt lgkmcnt(2)
	v_mfma_f32_32x32x16_bf16 v[18:33], v[38:41], v[34:37], v[18:33]
	v_add_f32_e64 v38, v162, v82
	v_add_f32_e64 v39, v163, v83
	v_add_f32_e64 v54, v166, v84
	v_add_f32_e64 v55, v167, v85
	v_add_f32_e64 v48, v38, v48
	v_add_f32_e64 v49, v39, v49
	v_pk_add_f32 v[38:39], v[164:165], v[72:73]
	v_pk_add_f32 v[52:53], v[54:55], v[52:53]
	v_pk_add_f32 v[50:51], v[38:39], v[50:51]
	ds_read_b64_tr_b16 v[38:39], v0 offset:48384
	ds_read_b64_tr_b16 v[40:41], v0 offset:49536
	s_waitcnt lgkmcnt(2)
	v_mfma_f32_32x32x16_bf16 v[2:17], v[42:45], v[34:37], v[2:17]
	ds_read_b64_tr_b16 v[44:45], v0 offset:49600
	ds_read_b64_tr_b16 v[42:43], v0 offset:48448
	v_cvt_pk_bf16_f32 v34, v155, v163
	v_cvt_pk_bf16_f32 v35, v165, v167
	v_cvt_pk_bf16_f32 v36, v159, v161
	v_cvt_pk_bf16_f32 v37, v169, v91
	v_pk_add_f32 v[54:55], v[168:169], v[76:77]
	s_waitcnt lgkmcnt(2)
	v_mfma_f32_32x32x16_bf16 v[18:33], v[38:41], v[34:37], v[18:33]
	v_add_f32_e64 v38, v158, v74
	v_add_f32_e64 v39, v159, v75
	v_add_f32_e64 v50, v54, v50
	v_add_f32_e64 v51, v55, v51
	v_add_f32_e64 v46, v38, v46
	v_add_f32_e64 v47, v39, v47
	v_pk_add_f32 v[38:39], v[160:161], v[86:87]
	s_nop 0
	v_pk_add_f32 v[48:49], v[38:39], v[48:49]
	ds_read_b64_tr_b16 v[38:39], v0 offset:50688
	ds_read_b64_tr_b16 v[40:41], v0 offset:51840
	s_waitcnt lgkmcnt(2)
	v_mfma_f32_32x32x16_bf16 v[2:17], v[42:45], v[34:37], v[2:17]
	ds_read_b64_tr_b16 v[44:45], v0 offset:51904
	ds_read_b64_tr_b16 v[42:43], v0 offset:50752
	v_cvt_pk_bf16_f32 v34, v79, v129
	v_cvt_pk_bf16_f32 v35, v81, v137
	v_cvt_pk_bf16_f32 v36, v139, v141
	v_cvt_pk_bf16_f32 v37, v143, v145
	s_waitcnt lgkmcnt(2)
	s_nop 0
	v_mfma_f32_32x32x16_bf16 v[18:33], v[38:41], v[34:37], v[18:33]
	v_add_f32_e64 v38, v90, v88
	v_add_f32_e64 v39, v91, v89
	v_add_f32_e64 v40, v46, v48
	v_add_f32_e64 v41, v47, v49
	v_add_f32_e64 v38, v38, v52
	v_add_f32_e64 v39, v39, v53
	v_pk_add_f32 v[38:39], v[50:51], v[38:39]
	s_nop 0
	v_pk_add_f32 v[46:47], v[40:41], v[38:39]
	s_waitcnt lgkmcnt(0)
	v_mfma_f32_32x32x16_bf16 v[2:17], v[42:45], v[34:37], v[2:17]
	ds_read_b64_tr_b16 v[38:39], v0 offset:52992
	ds_read_b64_tr_b16 v[40:41], v0 offset:54144
	ds_read_b64_tr_b16 v[44:45], v0 offset:54208
	ds_read_b64_tr_b16 v[42:43], v0 offset:53056
	v_cvt_pk_bf16_f32 v34, v71, v83
	v_cvt_pk_bf16_f32 v35, v73, v85
	v_cvt_pk_bf16_f32 v36, v75, v87
	v_cvt_pk_bf16_f32 v37, v77, v89
	v_add_f32_e32 v46, v217, v46
	v_add_f32_e32 v217, v46, v47
	s_waitcnt lgkmcnt(2)
	v_mfma_f32_32x32x16_bf16 v[18:33], v[38:41], v[34:37], v[18:33]
	s_waitcnt lgkmcnt(0)
	s_barrier
	v_mfma_f32_32x32x16_bf16 v[2:17], v[42:45], v[34:37], v[2:17]
	s_waitcnt vmcnt(9)
	v_mov_b32_e32 v35, v123
	s_cbranch_scc1 .LBB0_707
.LBB0_704:
	s_add_i32 s1, s34, 1
	s_and_b32 s21, s1, 1
	s_mul_i32 s23, s21, 0x4800
	v_add_u32_e32 v0, s23, v210
	v_add_f32_e32 v34, v218, v122
	ds_write_b128 v0, v[94:97]
	s_waitcnt vmcnt(6)
	ds_write_b128 v0, v[98:101] offset:36864
	s_waitcnt vmcnt(5)
	ds_write_b128 v0, v[102:105] offset:9216
	ds_write_b128 v0, v[106:109] offset:46080
	v_sub_f32_e32 v0, v218, v117
	v_lshl_add_u32 v36, s21, 12, v211
	v_sub_f32_e32 v37, v34, v117
	s_add_i32 s21, s34, 2
	v_add_f32_e32 v0, v0, v215
	s_waitcnt vmcnt(4)
	v_add_f32_e32 v37, v216, v37
	s_cmp_ge_u32 s21, s25
	ds_write2st64_b32 v36, v0, v37 offset1:8
	s_cbranch_scc1 .LBB0_703
	v_add_u32_e32 v36, s0, v178
	v_ashrrev_i32_e32 v37, 31, v36
	v_lshlrev_b64 v[38:39], 13, v[36:37]
	v_add_u32_e32 v36, 64, v36
	v_ashrrev_i32_e32 v37, 31, v36
	s_lshl_b64 s[30:31], s[86:87], 2
	v_lshlrev_b64 v[36:37], 13, v[36:37]
	v_lshl_add_u64 v[40:41], v[124:125], 0, v[38:39]
	s_add_u32 s30, s26, s30
	v_add_u32_e32 v0, s0, v110
	v_lshl_add_u64 v[42:43], v[124:125], 0, v[36:37]
	v_lshl_add_u64 v[38:39], v[126:127], 0, v[38:39]
	s_addc_u32 s31, s27, s31
	global_load_dwordx4 v[94:97], v[40:41], off offset:2048
	global_load_dwordx2 v[122:123], v1, s[30:31]
	s_mov_b64 s[30:31], 0x300000
	v_lshl_add_u64 v[44:45], v[40:41], 0, s[30:31]
	v_lshl_add_u64 v[40:41], v[0:1], 2, s[28:29]
	v_lshl_add_u64 v[36:37], v[126:127], 0, v[36:37]
	global_load_dwordx4 v[102:105], v[42:43], off offset:2048
	global_load_dwordx4 v[106:109], v[36:37], off
	global_load_dwordx4 v[98:101], v[38:39], off
	global_load_dword v215, v[40:41], off
	global_load_dword v216, v[40:41], off offset:256
	v_lshl_add_u64 v[42:43], v[42:43], 0, s[30:31]
	v_lshl_add_u64 v[36:37], v[36:37], 0, s[30:31]
	v_lshl_add_u64 v[38:39], v[38:39], 0, s[30:31]
	global_load_dword v219, v[44:45], off offset:2048
	global_load_dword v219, v[42:43], off offset:2048
	global_load_dword v219, v[36:37], off
	global_load_dword v219, v[38:39], off
	s_branch .LBB0_703
